# q4 filler sliding-window items: hand-written attention loop with K/V tiles staged per workgroup in LDS by DMA (block streams the union of the 8 windows), direct bias table, window/causal masks only on
# speedup vs baseline: 1.0108x; 1.0019x over previous
; #define TIDX get_tid_()
; DI void nsa_win_item(const Params& p, int b, int head, int qb, const unsigned char* blut, const float* tbl) {
;   const int lane = TIDX & 63, r = lane & 31, h = lane >> 5;
;   const int g = head / 3, bg = b * 2 + g;
;   const int t = qb * 32 + r;
;   const float* tblh = tbl + head * 32;
;   bf16x8 qf[4];
;   load_q(qf, (const bf16_t*)(p.ws + OFF_QN) + (size_t)(b * 4096 + t) * 384 + head * 64 + 8 * h);
;   const float g2 = ((const float*)(p.ws + OFF_GATES))[(size_t)(b * 4096 + t) * 18 + head * 3 + 2];
;   f32x16 y0, y1;
; #pragma unroll
;   for (int i = 0; i < 16; ++i) { y0[i] = 0.f; y1[i] = 0.f; }
;   {
;     const bf16_t* K = (const bf16_t*)(p.ws + OFF_KWIN) + (size_t)bg * 4096 * 64;
;     const bf16_t* Vt = (const bf16_t*)(p.ws + OFF_VWINT) + (size_t)bg * 64 * 4096;
;     AttnSt st; attn_init(st);
;     const int k0 = qb >= 16 ? qb - 16 : 0;
;     attn_loop(st, qf, k0, qb, 32,
; DI void filler_items(const Params& p, int layer, char* lds, int which) {
;     ...
;       else { const int it2 = item - 128 * 16, qb = 127 - it2 / 48, sub = it2 % 48; nsa_win_item(p, sub / 6, sub % 6, qb, blut, tbl); }
.Lf4_done:
	v_mov_b32_e32 v4, s14
	s_movk_i32 s8, 0x1a00
	s_waitcnt lgkmcnt(0)
	v_cmp_gt_i32_e32 vcc, s8, v4
	s_mov_b64 s[8:9], -1
	s_and_saveexec_b64 s[14:15], vcc
	s_cbranch_execz .LBB0_1024
	s_movk_i32 s8, 0x7ff
	v_cmp_lt_i32_e32 vcc, s8, v4
	s_and_saveexec_b64 s[8:9], vcc
	s_xor_b64 s[8:9], exec, s[8:9]
	s_cbranch_execz .LBB0_1039
	v_add_u16_e32 v0, 0xf800, v4
	v_mul_u32_u24_e32 v1, 0xaaab, v0
	v_lshrrev_b32_e32 v30, 21, v1
	s_movk_i32 s23, 0x7f
	v_mul_lo_u16_e32 v1, 48, v30
	v_sub_u32_sdwa v138, s23, v30 dst_sel:DWORD dst_unused:UNUSED_PAD src0_sel:DWORD src1_sel:WORD_0
	v_sub_u16_e32 v0, v0, v1
	s_movk_i32 s23, 0xab
	v_mul_lo_u16_sdwa v1, v0, s23 dst_sel:DWORD dst_unused:UNUSED_PAD src0_sel:BYTE_0 src1_sel:DWORD
	v_lshrrev_b16_e32 v2, 10, v1
	v_mul_lo_u16_e32 v1, 6, v2
	v_sub_u16_e32 v31, v0, v1
	v_mov_b32_e32 v0, v129
	v_readlane_b32 s24, v253, 13
	v_and_b32_e32 v32, 31, v0
	v_bfe_u32 v33, v0, 5, 1
	v_lshlrev_b32_e32 v0, 5, v138
	v_lshlrev_b32_e32 v1, 12, v2
	v_readlane_b32 s25, v253, 14
	v_or3_b32 v113, v32, v0, v1
	s_movk_i32 s23, 0x300
	v_mov_b64_e32 v[0:1], s[24:25]
	v_mad_u64_u32 v[0:1], s[26:27], v113, s23, v[0:1]
	v_lshlrev_b32_sdwa v130, v202, v31 dst_sel:DWORD dst_unused:UNUSED_PAD src0_sel:DWORD src1_sel:BYTE_0
	v_cmp_gt_u16_sdwa vcc, v31, v204 src0_sel:BYTE_0 src1_sel:DWORD
	v_lshl_add_u64 v[4:5], v[0:1], 0, v[130:131]
	v_readlane_b32 s24, v253, 31
	v_cndmask_b32_e32 v0, 0, v205, vcc
	v_add_u32_e32 v139, 0, v130
	v_lshl_or_b32 v130, v2, 20, v0
	v_readlane_b32 s25, v253, 32
	s_movk_i32 s23, 0x6f
	v_sub_u32_sdwa v0, s23, v30 dst_sel:DWORD dst_unused:UNUSED_PAD src0_sel:DWORD src1_sel:WORD_0
	v_lshl_add_u64 v[20:21], s[24:25], 0, v[130:131]
	v_readlane_b32 s24, v253, 33
	v_readlane_b32 s25, v253, 34
	v_lshlrev_b32_e32 v2, 3, v32
	v_lshl_or_b32 v24, v33, 8, v2
	v_lshl_add_u64 v[22:23], s[24:25], 0, v[130:131]
	v_lshlrev_b32_e32 v130, 12, v0
	v_lshl_add_u64 v[0:1], v[20:21], 0, v[130:131]
	v_lshlrev_b32_e32 v26, 1, v24
	v_mov_b32_e32 v27, v131
	v_lshl_add_u64 v[12:13], v[0:1], 0, v[26:27]
	global_load_dwordx4 v[0:3], v[12:13], off
	v_lshlrev_b32_e32 v6, 4, v33
	v_mov_b32_e32 v7, v131
	v_lshl_add_u64 v[14:15], v[4:5], 0, v[6:7]
	global_load_dwordx4 v[64:67], v[14:15], off
	global_load_dwordx4 v[68:71], v[14:15], off offset:32
	global_load_dwordx4 v[4:7], v[12:13], off offset:1024
	v_readlane_b32 s24, v253, 29
	v_readlane_b32 s25, v253, 30
	v_lshlrev_b32_sdwa v10, v209, v30 dst_sel:DWORD dst_unused:UNUSED_PAD src0_sel:DWORD src1_sel:WORD_0
	v_sub_u32_e32 v16, 0x70000, v10
	v_mov_b64_e32 v[8:9], s[24:25]
	v_mul_u32_u24_sdwa v10, v31, v203 dst_sel:DWORD dst_unused:UNUSED_PAD src0_sel:BYTE_0 src1_sel:DWORD
	s_movk_i32 s23, 0x48
	v_mov_b32_e32 v11, v131
	v_mad_u64_u32 v[8:9], s[26:27], v113, s23, v[8:9]
	v_lshlrev_b32_e32 v10, 2, v10
	v_lshl_add_u64 v[18:19], v[8:9], 0, v[10:11]
	global_load_dwordx4 v[8:11], v[12:13], off offset:2048
	global_load_dwordx4 v[72:75], v[14:15], off offset:64
	global_load_dwordx4 v[76:79], v[14:15], off offset:96
	v_mov_b32_e32 v17, v131
	v_lshl_add_u64 v[14:15], v[20:21], 0, v[16:17]
	v_mov_b32_e32 v25, v131
	v_lshl_add_u64 v[16:17], v[22:23], 0, v[130:131]
	v_lshl_add_u64 v[14:15], v[14:15], 0, v[26:27]
	v_lshl_add_u64 v[28:29], v[16:17], 0, v[24:25]
	global_load_dword v140, v[18:19], off
	s_nop 0
	global_load_dwordx4 v[16:19], v[12:13], off offset:3072
	global_load_dwordx4 v[88:91], v[14:15], off offset:2048
	global_load_dwordx4 v[84:87], v[14:15], off offset:1024
	global_load_dwordx4 v[92:95], v[14:15], off
	global_load_dwordx2 v[82:83], v[28:29], off offset:3584
	global_load_dwordx2 v[80:81], v[28:29], off offset:3072
	global_load_dwordx2 v[98:99], v[28:29], off offset:2560
	global_load_dwordx2 v[96:97], v[28:29], off offset:2048
	global_load_dwordx2 v[106:107], v[28:29], off offset:1536
	global_load_dwordx2 v[104:105], v[28:29], off offset:1024
	global_load_dwordx2 v[110:111], v[28:29], off offset:512
	global_load_dwordx4 v[100:103], v[14:15], off offset:3072
	global_load_dwordx2 v[108:109], v[28:29], off
	s_mov_b32 s56, 0
	s_mov_b32 s57, s56
	s_mov_b32 s58, s56
	s_mov_b32 s59, s56
	s_mov_b32 s60, s56
	s_mov_b32 s61, s56
	s_mov_b32 s62, s56
	s_mov_b32 s63, s56
	s_mov_b32 s64, s56
	s_mov_b32 s65, s56
	s_mov_b32 s66, s56
	s_mov_b32 s67, s56
	s_mov_b32 s68, s56
	s_mov_b32 s69, s56
	s_mov_b32 s70, s56
	s_mov_b32 s71, s56
	s_movk_i32 s23, 0x71
	v_lshlrev_b32_sdwa v112, v201, v31 dst_sel:DWORD dst_unused:UNUSED_PAD src0_sel:DWORD src1_sel:BYTE_0
	v_lshl_add_u64 v[114:115], v[22:23], 0, v[24:25]
	v_lshl_add_u64 v[116:117], v[20:21], 0, v[26:27]
	v_lshlrev_b32_e32 v141, 2, v33
	v_sub_u32_sdwa v143, s23, v30 dst_sel:DWORD dst_unused:UNUSED_PAD src0_sel:DWORD src1_sel:WORD_0
	v_sub_u32_e32 v142, v32, v141
	v_mov_b32_e32 v144, 0
	v_mov_b32_e32 v145, 0xff800000
	s_waitcnt vmcnt(19)
	v_mfma_f32_32x32x16_bf16 v[48:63], v[0:3], v[64:67], 0
	s_waitcnt vmcnt(17)
	v_mfma_f32_32x32x16_bf16 v[48:63], v[4:7], v[68:71], v[48:63]
	s_waitcnt vmcnt(15)
	v_mfma_f32_32x32x16_bf16 v[48:63], v[8:11], v[72:75], v[48:63]
	v_mov_b64_e32 v[0:1], s[56:57]
	v_mov_b64_e32 v[14:15], s[70:71]
	v_mov_b64_e32 v[2:3], s[58:59]
	v_mov_b64_e32 v[4:5], s[60:61]
	v_mov_b64_e32 v[6:7], s[62:63]
	v_mov_b64_e32 v[8:9], s[64:65]
	v_mov_b64_e32 v[10:11], s[66:67]
	s_waitcnt vmcnt(12)
	v_mfma_f32_32x32x16_bf16 v[48:63], v[16:19], v[76:79], v[48:63]
	v_mov_b64_e32 v[12:13], s[68:69]
	v_mov_b64_e32 v[30:31], v[14:15]
	v_mov_b64_e32 v[28:29], v[12:13]
	v_mov_b64_e32 v[26:27], v[10:11]
	v_mov_b64_e32 v[24:25], v[8:9]
	v_mov_b64_e32 v[22:23], v[6:7]
	v_mov_b64_e32 v[20:21], v[4:5]
	v_mov_b64_e32 v[18:19], v[2:3]
	v_mov_b64_e32 v[16:17], v[0:1]
	s_waitcnt vmcnt(0)
	v_readfirstlane_b32 s60, v138
	v_lshrrev_b32_e32 v184, 6, v129
	v_and_b32_e32 v185, 63, v129
	v_lshlrev_b32_e32 v185, 3, v185
	v_readfirstlane_b32 s58, v184
	s_sub_u32 s65, s60, 16
	s_cmp_lt_u32 s60, 16
	s_cselect_b32 s65, 0, s65
	s_mov_b64 s[62:63], -1
	v_mov_b32_e32 v32, s60
	v_mov_b32_e32 v33, 0x1940
	v_lshl_add_u32 v42, v184, 2, v33
	ds_write_b32 v42, v32
	s_waitcnt lgkmcnt(0)
	s_barrier
; #define MFMA32(a, b, c) __builtin_amdgcn_mfma_f32_32x32x16_bf16((a), (b), (c), 0, 0, 0)
; template <class KP, class VP, class ACT, class FILL>
; DI void attn_loop(AttnSt& st, const bf16x8 (&qf)[4], int k0, int k1, size_t vstride, KP kp, VP vp, ACT act, FILL fill) {
;     ...
;   for (int kt = k0; kt <= k1; ++kt) {
;     const int kn = (kt < k1) ? kt + 1 : k1;
;     const int kn2 = (kt + 2 <= k1) ? kt + 2 : k1;
;     {
;       const bf16_t* v0 = vp(kn);
; #pragma unroll
;       for (int j = 0; j < 8; ++j) nxt.v[j] = *(const s16x4*)(v0 + 256 * j);
;     }
;     bf16x8 k2[4];
;     {
;       const bf16_t* krow = kp(kn2);
; #pragma unroll
;       for (int ss = 0; ss < 4; ++ss) k2[ss] = *(const bf16x8*)(krow + 512 * ss);
;     }
;     f32x16 s_next;
; #pragma unroll
;     for (int i = 0; i < 16; ++i) s_next[i] = 0.f;
; #pragma unroll
;     for (int ss = 0; ss < 4; ++ss) s_next = MFMA32(nxt.k[ss], qf[ss], s_next);
; DI void bias16(const unsigned char* blut, const float* tblh, const int (&dist)[16], float (&bv)[16]) {
;   int bk[16];
; #pragma unroll
;   for (int i = 0; i < 16; ++i) { const int d = dist[i] < 0 ? 0 : (dist[i] > 2048 ? 2048 : dist[i]); bk[i] = blut[d]; }
; #pragma unroll
;   for (int i = 0; i < 16; ++i) asm volatile("" : "+v"(bk[i]));
; #pragma unroll
;   for (int i = 0; i < 16; ++i) bv[i] = tblh[bk[i]];
; #pragma unroll
;   for (int i = 0; i < 16; ++i) asm volatile("" : "+v"(bv[i]));
; }
	ds_read_b128 v[34:37], v33
	ds_read_b128 v[38:41], v33 offset:16
	s_waitcnt lgkmcnt(0)
	v_min3_u32 v42, v34, v35, v36
	v_min3_u32 v42, v42, v37, v38
	v_min3_u32 v42, v42, v39, v40
	v_min_u32_e32 v42, v42, v41
	v_max3_u32 v34, v34, v35, v36
	v_max3_u32 v34, v34, v37, v38
	v_max3_u32 v34, v34, v39, v40
	v_max_u32_e32 v34, v34, v41
	s_nop 0
	v_readfirstlane_b32 s59, v34
	v_readfirstlane_b32 s66, v42
	s_sub_u32 s56, s66, 16
	s_cmp_lt_u32 s66, 16
	s_cselect_b32 s56, 0, s56
	s_and_b32 s56, s56, -2
	s_lshr_b32 s23, s56, 1
	s_mov_b32 s64, 0x10000
	s_lshr_b32 s24, s59, 1
	s_min_u32 s24, s23, s24
	s_lshl_b32 s26, s24, 13
	s_lshl_b32 s24, s58, 10
	s_add_u32 s26, s26, s24
	s_mov_b32 s27, 0
	v_lshl_add_u64 v[186:187], v[116:117], 0, s[26:27]
	v_lshl_add_u64 v[126:127], v[114:115], 0, s[26:27]
	v_add_co_u32_e32 v126, vcc, v126, v185
	v_addc_co_u32_e32 v127, vcc, 0, v127, vcc
	s_add_u32 s24, s24, s64
	s_mov_b32 m0, s24
	s_nop 0
	global_load_lds_dwordx4 v[186:187], off
	s_add_u32 s24, s24, 0x2000
	s_mov_b32 m0, s24
	s_nop 0
	global_load_lds_dwordx4 v[126:127], off
	s_lshr_b32 s23, s56, 1
	s_add_u32 s23, s23, 1
	s_mov_b32 s64, 0x14000
	s_lshr_b32 s24, s59, 1
	s_min_u32 s24, s23, s24
	s_lshl_b32 s26, s24, 13
	s_lshl_b32 s24, s58, 10
	s_add_u32 s26, s26, s24
	s_mov_b32 s27, 0
	v_lshl_add_u64 v[186:187], v[116:117], 0, s[26:27]
	v_lshl_add_u64 v[126:127], v[114:115], 0, s[26:27]
	v_add_co_u32_e32 v126, vcc, v126, v185
	v_addc_co_u32_e32 v127, vcc, 0, v127, vcc
	s_add_u32 s24, s24, s64
	s_mov_b32 m0, s24
	s_nop 0
	global_load_lds_dwordx4 v[186:187], off
	s_add_u32 s24, s24, 0x2000
	s_mov_b32 m0, s24
	s_nop 0
	global_load_lds_dwordx4 v[126:127], off
	s_mov_b32 s64, 0x10000
	v_lshrrev_b32_e32 v184, 6, v129
	v_mul_u32_u24_e32 v184, 6912, v184
	v_add_u32_e32 v180, 8192, v184
	v_and_b32_e32 v184, 63, v129
	v_mov_b32_e32 v80, 0
	v_mov_b32_e32 v81, v184
	v_add_u32_e32 v82, 64, v184
	v_add_u32_e32 v83, 128, v184
	v_add_u32_e32 v84, 192, v184
	v_add_u32_e32 v85, 256, v184
	v_add_u32_e32 v86, 320, v184
	v_add_u32_e32 v87, 384, v184
	v_add_u32_e32 v88, 448, v184
	v_add_u32_e32 v89, 512, v184
	ds_read_u8 v80, v80
	ds_read_u8 v81, v81
	ds_read_u8 v82, v82
	ds_read_u8 v83, v83
	ds_read_u8 v84, v84
	ds_read_u8 v85, v85
	ds_read_u8 v86, v86
	ds_read_u8 v87, v87
	ds_read_u8 v88, v88
	ds_read_u8 v89, v89
	s_waitcnt lgkmcnt(9)
	v_lshl_add_u32 v80, v80, 2, v139
	s_waitcnt lgkmcnt(8)
	v_lshl_add_u32 v81, v81, 2, v139
	s_waitcnt lgkmcnt(7)
	v_lshl_add_u32 v82, v82, 2, v139
	s_waitcnt lgkmcnt(6)
	v_lshl_add_u32 v83, v83, 2, v139
	s_waitcnt lgkmcnt(5)
	v_lshl_add_u32 v84, v84, 2, v139
	s_waitcnt lgkmcnt(4)
	v_lshl_add_u32 v85, v85, 2, v139
	s_waitcnt lgkmcnt(3)
	v_lshl_add_u32 v86, v86, 2, v139
	s_waitcnt lgkmcnt(2)
	v_lshl_add_u32 v87, v87, 2, v139
	s_waitcnt lgkmcnt(1)
	v_lshl_add_u32 v88, v88, 2, v139
	s_waitcnt lgkmcnt(0)
	v_lshl_add_u32 v89, v89, 2, v139
	ds_read_b32 v80, v80 offset:4096
	ds_read_b32 v81, v81 offset:4096
	ds_read_b32 v82, v82 offset:4096
	ds_read_b32 v83, v83 offset:4096
	ds_read_b32 v84, v84 offset:4096
	ds_read_b32 v85, v85 offset:4096
	ds_read_b32 v86, v86 offset:4096
	ds_read_b32 v87, v87 offset:4096
	ds_read_b32 v88, v88 offset:4096
	ds_read_b32 v89, v89 offset:4096
	v_lshl_add_u32 v182, v184, 2, v180
	s_waitcnt lgkmcnt(0)
	ds_write_b32 v182, v80 offset:0
	s_waitcnt lgkmcnt(0)
	ds_write_b32 v182, v81 offset:256
	s_waitcnt lgkmcnt(0)
	ds_write_b32 v182, v82 offset:512
	s_waitcnt lgkmcnt(0)
	ds_write_b32 v182, v83 offset:768
	s_waitcnt lgkmcnt(0)
	ds_write_b32 v182, v84 offset:1024
	s_waitcnt lgkmcnt(0)
	ds_write_b32 v182, v85 offset:1280
	s_waitcnt lgkmcnt(0)
	ds_write_b32 v182, v86 offset:1536
	s_waitcnt lgkmcnt(0)
	ds_write_b32 v182, v87 offset:1792
	s_waitcnt lgkmcnt(0)
	ds_write_b32 v182, v88 offset:2048
	s_waitcnt lgkmcnt(0)
	ds_write_b32 v182, v89 offset:2304
	ds_read_b32 v178, v139 offset:4220
	v_add_u32_e32 v180, 148, v180
	v_mov_b32_e32 v181, 0x7f800000
	s_waitcnt lgkmcnt(0)
.Lawin4_loop:
	s_waitcnt vmcnt(2)
	s_barrier
	s_lshr_b32 s23, s56, 1
	s_add_u32 s23, s23, 2
	s_sub_u32 s61, s64, 0x4000
	s_cmp_lt_u32 s61, 0x10000
	s_cselect_b32 s61, 0x18000, s61
	s_lshr_b32 s24, s59, 1
	s_min_u32 s24, s23, s24
	s_lshl_b32 s26, s24, 13
	s_lshl_b32 s24, s58, 10
	s_add_u32 s26, s26, s24
	s_mov_b32 s27, 0
	v_lshl_add_u64 v[186:187], v[116:117], 0, s[26:27]
	v_lshl_add_u64 v[126:127], v[114:115], 0, s[26:27]
	v_add_co_u32_e32 v126, vcc, v126, v185
	v_addc_co_u32_e32 v127, vcc, 0, v127, vcc
	s_add_u32 s24, s24, s61
	s_mov_b32 m0, s24
	s_nop 0
	global_load_lds_dwordx4 v[186:187], off
	s_add_u32 s24, s24, 0x2000
	s_mov_b32 m0, s24
	s_nop 0
	global_load_lds_dwordx4 v[126:127], off
	s_cmp_le_u32 s56, s60
	s_cbranch_scc0 .Lawin4_skip
	s_add_u32 s24, s56, 1
	s_cmp_ge_u32 s24, s65
	s_cbranch_scc0 .Lawin4_skip
	v_lshl_add_u32 v186, v185, 1, s64
	ds_read_b128 v[80:83], v186 offset:0
	ds_read_b128 v[84:87], v186 offset:1024
	ds_read_b128 v[88:91], v186 offset:2048
	ds_read_b128 v[92:95], v186 offset:3072
	ds_read_b128 v[96:99], v186 offset:4096
	ds_read_b128 v[100:103], v186 offset:5120
	ds_read_b128 v[104:107], v186 offset:6144
	ds_read_b128 v[108:111], v186 offset:7168
	s_sub_i32 s61, s60, s56
	s_waitcnt lgkmcnt(0)
	v_mfma_f32_32x32x16_bf16 v[32:47], v[80:83], v[64:67], 0
	v_mfma_f32_32x32x16_bf16 v[48:63], v[96:99], v[64:67], 0
	v_mfma_f32_32x32x16_bf16 v[32:47], v[84:87], v[68:71], v[32:47]
	v_mfma_f32_32x32x16_bf16 v[48:63], v[100:103], v[68:71], v[48:63]
	v_mfma_f32_32x32x16_bf16 v[32:47], v[88:91], v[72:75], v[32:47]
	v_mfma_f32_32x32x16_bf16 v[48:63], v[104:107], v[72:75], v[48:63]
	v_mfma_f32_32x32x16_bf16 v[32:47], v[92:95], v[76:79], v[32:47]
	v_mfma_f32_32x32x16_bf16 v[48:63], v[108:111], v[76:79], v[48:63]
	v_add_u32_e32 v126, s64, v185
	ds_read_b64 v[146:147], v126 offset:8192
	ds_read_b64 v[148:149], v126 offset:8704
	ds_read_b64 v[150:151], v126 offset:9216
	ds_read_b64 v[152:153], v126 offset:9728
	ds_read_b64 v[154:155], v126 offset:10240
	ds_read_b64 v[156:157], v126 offset:10752
	ds_read_b64 v[158:159], v126 offset:11264
	ds_read_b64 v[160:161], v126 offset:11776
	ds_read_b64 v[162:163], v126 offset:12288
	ds_read_b64 v[164:165], v126 offset:12800
	ds_read_b64 v[166:167], v126 offset:13312
	ds_read_b64 v[168:169], v126 offset:13824
	ds_read_b64 v[170:171], v126 offset:14336
	ds_read_b64 v[172:173], v126 offset:14848
	ds_read_b64 v[174:175], v126 offset:15360
	ds_read_b64 v[176:177], v126 offset:15872
	s_cmp_ge_i32 s61, 50
	s_cbranch_scc1 .Lawin4_far
; #define NEGINF (-__builtin_inff())
; DI int crow(int i, int h) { return (i & 3) + 8 * (i >> 2) + 4 * h; }
; DI void nsa_win_item(const Params& p, int b, int head, int qb, const unsigned char* blut, const float* tbl) {
;     ...
;       [&](int kt, const f32x16& s, float (&lg)[16]) {
;         int dist[16]; float bv[16];
; #pragma unroll
;         for (int i = 0; i < 16; ++i) dist[i] = t - (kt * 32 + crow(i, h));
;         bias16(blut, tblh, dist, bv);
; #pragma unroll
;         for (int i = 0; i < 16; ++i) lg[i] = (dist[i] >= 0 && dist[i] < 512) ? s[i] + bv[i] : NEGINF;
	s_lshl_b32 s23, s61, 5
	v_add_u32_e32 v179, s23, v142
	v_lshl_add_u32 v182, v179, 2, v180
	v_subrev_u32_e32 v183, 128, v182
	ds_read_b32 v118, v182 offset:108
	ds_read_b32 v119, v182 offset:104
	ds_read_b32 v120, v182 offset:100
	ds_read_b32 v121, v182 offset:96
	ds_read_b32 v122, v182 offset:76
	ds_read_b32 v123, v182 offset:72
	ds_read_b32 v124, v182 offset:68
	ds_read_b32 v125, v182 offset:64
	ds_read_b32 v132, v182 offset:44
	ds_read_b32 v133, v182 offset:40
	ds_read_b32 v134, v182 offset:36
	ds_read_b32 v135, v182 offset:32
	ds_read_b32 v218, v182 offset:12
	ds_read_b32 v219, v182 offset:8
	ds_read_b32 v220, v182 offset:4
	ds_read_b32 v221, v182 offset:0
	s_waitcnt lgkmcnt(8)
	v_add_f32_e32 v32, v32, v118
	v_add_f32_e32 v33, v33, v119
	v_add_f32_e32 v34, v34, v120
	v_add_f32_e32 v35, v35, v121
	v_add_f32_e32 v36, v36, v122
	v_add_f32_e32 v37, v37, v123
	v_add_f32_e32 v38, v38, v124
	v_add_f32_e32 v39, v39, v125
	s_waitcnt lgkmcnt(0)
	v_add_f32_e32 v40, v40, v132
	v_add_f32_e32 v41, v41, v133
	v_add_f32_e32 v42, v42, v134
	v_add_f32_e32 v43, v43, v135
	v_add_f32_e32 v44, v44, v218
	v_add_f32_e32 v45, v45, v219
	v_add_f32_e32 v46, v46, v220
	v_add_f32_e32 v47, v47, v221
	ds_read_b32 v118, v183 offset:108
	ds_read_b32 v119, v183 offset:104
	ds_read_b32 v120, v183 offset:100
	ds_read_b32 v121, v183 offset:96
	ds_read_b32 v122, v183 offset:76
	ds_read_b32 v123, v183 offset:72
	ds_read_b32 v124, v183 offset:68
	ds_read_b32 v125, v183 offset:64
	ds_read_b32 v132, v183 offset:44
	ds_read_b32 v133, v183 offset:40
	ds_read_b32 v134, v183 offset:36
	ds_read_b32 v135, v183 offset:32
	ds_read_b32 v218, v183 offset:12
	ds_read_b32 v219, v183 offset:8
	ds_read_b32 v220, v183 offset:4
	ds_read_b32 v221, v183 offset:0
	s_waitcnt lgkmcnt(8)
	v_add_f32_e32 v48, v48, v118
	v_add_f32_e32 v49, v49, v119
	v_add_f32_e32 v50, v50, v120
	v_add_f32_e32 v51, v51, v121
	v_add_f32_e32 v52, v52, v122
	v_add_f32_e32 v53, v53, v123
	v_add_f32_e32 v54, v54, v124
	v_add_f32_e32 v55, v55, v125
	s_waitcnt lgkmcnt(0)
	v_add_f32_e32 v56, v56, v132
	v_add_f32_e32 v57, v57, v133
	v_add_f32_e32 v58, v58, v134
	v_add_f32_e32 v59, v59, v135
	v_add_f32_e32 v60, v60, v218
	v_add_f32_e32 v61, v61, v219
	v_add_f32_e32 v62, v62, v220
	v_add_f32_e32 v63, v63, v221
	s_cmp_ge_i32 s61, 15
	s_cbranch_scc0 .Lawin4_nowin
	v_subrev_u32_e32 v184, 32, v179
	v_cmp_gt_i32_e32 vcc, 0x200, v179
	s_nop 1
	v_cndmask_b32_e32 v32, v199, v32, vcc
	v_cmp_gt_i32_e32 vcc, 0x201, v179
	s_nop 1
	v_cndmask_b32_e32 v33, v199, v33, vcc
	v_cmp_gt_i32_e32 vcc, 0x202, v179
	s_nop 1
	v_cndmask_b32_e32 v34, v199, v34, vcc
	v_cmp_gt_i32_e32 vcc, 0x203, v179
	s_nop 1
	v_cndmask_b32_e32 v35, v199, v35, vcc
	v_cmp_gt_i32_e32 vcc, 0x208, v179
	s_nop 1
	v_cndmask_b32_e32 v36, v199, v36, vcc
	v_cmp_gt_i32_e32 vcc, 0x209, v179
	s_nop 1
	v_cndmask_b32_e32 v37, v199, v37, vcc
	v_cmp_gt_i32_e32 vcc, 0x20a, v179
	s_nop 1
	v_cndmask_b32_e32 v38, v199, v38, vcc
	v_cmp_gt_i32_e32 vcc, 0x20b, v179
	s_nop 1
	v_cndmask_b32_e32 v39, v199, v39, vcc
	v_cmp_gt_i32_e32 vcc, 0x210, v179
	s_nop 1
	v_cndmask_b32_e32 v40, v199, v40, vcc
	v_cmp_gt_i32_e32 vcc, 0x211, v179
	s_nop 1
	v_cndmask_b32_e32 v41, v199, v41, vcc
	v_cmp_gt_i32_e32 vcc, 0x212, v179
	s_nop 1
	v_cndmask_b32_e32 v42, v199, v42, vcc
	v_cmp_gt_i32_e32 vcc, 0x213, v179
	s_nop 1
	v_cndmask_b32_e32 v43, v199, v43, vcc
	v_cmp_gt_i32_e32 vcc, 0x218, v179
	s_nop 1
	v_cndmask_b32_e32 v44, v199, v44, vcc
	v_cmp_gt_i32_e32 vcc, 0x219, v179
	s_nop 1
	v_cndmask_b32_e32 v45, v199, v45, vcc
	v_cmp_gt_i32_e32 vcc, 0x21a, v179
	s_nop 1
	v_cndmask_b32_e32 v46, v199, v46, vcc
	v_cmp_gt_i32_e32 vcc, 0x21b, v179
	s_nop 1
	v_cndmask_b32_e32 v47, v199, v47, vcc
	v_cmp_gt_i32_e32 vcc, 0x200, v184
	s_nop 1
	v_cndmask_b32_e32 v48, v199, v48, vcc
	v_cmp_gt_i32_e32 vcc, 0x201, v184
	s_nop 1
	v_cndmask_b32_e32 v49, v199, v49, vcc
	v_cmp_gt_i32_e32 vcc, 0x202, v184
	s_nop 1
	v_cndmask_b32_e32 v50, v199, v50, vcc
	v_cmp_gt_i32_e32 vcc, 0x203, v184
	s_nop 1
	v_cndmask_b32_e32 v51, v199, v51, vcc
	v_cmp_gt_i32_e32 vcc, 0x208, v184
	s_nop 1
	v_cndmask_b32_e32 v52, v199, v52, vcc
	v_cmp_gt_i32_e32 vcc, 0x209, v184
	s_nop 1
	v_cndmask_b32_e32 v53, v199, v53, vcc
	v_cmp_gt_i32_e32 vcc, 0x20a, v184
	s_nop 1
	v_cndmask_b32_e32 v54, v199, v54, vcc
	v_cmp_gt_i32_e32 vcc, 0x20b, v184
	s_nop 1
	v_cndmask_b32_e32 v55, v199, v55, vcc
	v_cmp_gt_i32_e32 vcc, 0x210, v184
	s_nop 1
	v_cndmask_b32_e32 v56, v199, v56, vcc
	v_cmp_gt_i32_e32 vcc, 0x211, v184
	s_nop 1
	v_cndmask_b32_e32 v57, v199, v57, vcc
	v_cmp_gt_i32_e32 vcc, 0x212, v184
	s_nop 1
	v_cndmask_b32_e32 v58, v199, v58, vcc
	v_cmp_gt_i32_e32 vcc, 0x213, v184
	s_nop 1
	v_cndmask_b32_e32 v59, v199, v59, vcc
	v_cmp_gt_i32_e32 vcc, 0x218, v184
	s_nop 1
	v_cndmask_b32_e32 v60, v199, v60, vcc
	v_cmp_gt_i32_e32 vcc, 0x219, v184
	s_nop 1
	v_cndmask_b32_e32 v61, v199, v61, vcc
	v_cmp_gt_i32_e32 vcc, 0x21a, v184
	s_nop 1
	v_cndmask_b32_e32 v62, v199, v62, vcc
	v_cmp_gt_i32_e32 vcc, 0x21b, v184
	s_nop 1
	v_cndmask_b32_e32 v63, v199, v63, vcc
; #define NEGINF (-__builtin_inff())
; DI int crow(int i, int h) { return (i & 3) + 8 * (i >> 2) + 4 * h; }
; DI void nsa_win_item(const Params& p, int b, int head, int qb, const unsigned char* blut, const float* tbl) {
;     ...
;       [&](int kt, const f32x16& s, float (&lg)[16]) {
;         int dist[16]; float bv[16];
; #pragma unroll
;         for (int i = 0; i < 16; ++i) dist[i] = t - (kt * 32 + crow(i, h));
;         bias16(blut, tblh, dist, bv);
; #pragma unroll
;         for (int i = 0; i < 16; ++i) lg[i] = (dist[i] >= 0 && dist[i] < 512) ? s[i] + bv[i] : NEGINF;
.Lawin4_nowin:
	s_cmp_ge_i32 s61, 2
	s_cbranch_scc1 .Lawin4_softmax
	v_subrev_u32_e32 v184, 32, v179
	v_cmp_le_i32_e32 vcc, 0, v179
	s_nop 1
	v_cndmask_b32_e32 v32, v199, v32, vcc
	v_cmp_le_i32_e32 vcc, 1, v179
	s_nop 1
	v_cndmask_b32_e32 v33, v199, v33, vcc
	v_cmp_le_i32_e32 vcc, 2, v179
	s_nop 1
	v_cndmask_b32_e32 v34, v199, v34, vcc
	v_cmp_le_i32_e32 vcc, 3, v179
	s_nop 1
	v_cndmask_b32_e32 v35, v199, v35, vcc
	v_cmp_le_i32_e32 vcc, 8, v179
	s_nop 1
	v_cndmask_b32_e32 v36, v199, v36, vcc
	v_cmp_le_i32_e32 vcc, 9, v179
	s_nop 1
	v_cndmask_b32_e32 v37, v199, v37, vcc
	v_cmp_le_i32_e32 vcc, 10, v179
	s_nop 1
	v_cndmask_b32_e32 v38, v199, v38, vcc
	v_cmp_le_i32_e32 vcc, 11, v179
	s_nop 1
	v_cndmask_b32_e32 v39, v199, v39, vcc
	v_cmp_le_i32_e32 vcc, 16, v179
	s_nop 1
	v_cndmask_b32_e32 v40, v199, v40, vcc
	v_cmp_le_i32_e32 vcc, 17, v179
	s_nop 1
	v_cndmask_b32_e32 v41, v199, v41, vcc
	v_cmp_le_i32_e32 vcc, 18, v179
	s_nop 1
	v_cndmask_b32_e32 v42, v199, v42, vcc
	v_cmp_le_i32_e32 vcc, 19, v179
	s_nop 1
	v_cndmask_b32_e32 v43, v199, v43, vcc
	v_cmp_le_i32_e32 vcc, 24, v179
	s_nop 1
	v_cndmask_b32_e32 v44, v199, v44, vcc
	v_cmp_le_i32_e32 vcc, 25, v179
	s_nop 1
	v_cndmask_b32_e32 v45, v199, v45, vcc
	v_cmp_le_i32_e32 vcc, 26, v179
	s_nop 1
	v_cndmask_b32_e32 v46, v199, v46, vcc
	v_cmp_le_i32_e32 vcc, 27, v179
	s_nop 1
	v_cndmask_b32_e32 v47, v199, v47, vcc
	v_cmp_le_i32_e32 vcc, 0, v184
	s_nop 1
	v_cndmask_b32_e32 v48, v199, v48, vcc
	v_cmp_le_i32_e32 vcc, 1, v184
	s_nop 1
	v_cndmask_b32_e32 v49, v199, v49, vcc
	v_cmp_le_i32_e32 vcc, 2, v184
	s_nop 1
	v_cndmask_b32_e32 v50, v199, v50, vcc
	v_cmp_le_i32_e32 vcc, 3, v184
	s_nop 1
	v_cndmask_b32_e32 v51, v199, v51, vcc
	v_cmp_le_i32_e32 vcc, 8, v184
	s_nop 1
	v_cndmask_b32_e32 v52, v199, v52, vcc
	v_cmp_le_i32_e32 vcc, 9, v184
	s_nop 1
	v_cndmask_b32_e32 v53, v199, v53, vcc
	v_cmp_le_i32_e32 vcc, 10, v184
	s_nop 1
	v_cndmask_b32_e32 v54, v199, v54, vcc
	v_cmp_le_i32_e32 vcc, 11, v184
	s_nop 1
	v_cndmask_b32_e32 v55, v199, v55, vcc
	v_cmp_le_i32_e32 vcc, 16, v184
	s_nop 1
	v_cndmask_b32_e32 v56, v199, v56, vcc
	v_cmp_le_i32_e32 vcc, 17, v184
	s_nop 1
	v_cndmask_b32_e32 v57, v199, v57, vcc
	v_cmp_le_i32_e32 vcc, 18, v184
	s_nop 1
	v_cndmask_b32_e32 v58, v199, v58, vcc
	v_cmp_le_i32_e32 vcc, 19, v184
	s_nop 1
	v_cndmask_b32_e32 v59, v199, v59, vcc
	v_cmp_le_i32_e32 vcc, 24, v184
	s_nop 1
	v_cndmask_b32_e32 v60, v199, v60, vcc
	v_cmp_le_i32_e32 vcc, 25, v184
	s_nop 1
	v_cndmask_b32_e32 v61, v199, v61, vcc
	v_cmp_le_i32_e32 vcc, 26, v184
	s_nop 1
	v_cndmask_b32_e32 v62, v199, v62, vcc
	v_cmp_le_i32_e32 vcc, 27, v184
	s_nop 1
	v_cndmask_b32_e32 v63, v199, v63, vcc
	s_branch .Lawin4_softmax

; #define MFMA32(a, b, c) __builtin_amdgcn_mfma_f32_32x32x16_bf16((a), (b), (c), 0, 0, 0)
; #define NEGINF (-__builtin_inff())
; DI float shx32(float v) { const auto r = __builtin_amdgcn_permlane32_swap(__float_as_uint(v), __float_as_uint(v), false, false); return __uint_as_float((threadIdx.x & 32) ? r[0] : r[1]); }
; DI float ex2(float x) { return __builtin_amdgcn_exp2f(x); }
; DI unsigned pack2(float a, float b) { unsigned r; asm("v_cvt_pk_bf16_f32 %0, %1, %2" : "=v"(r) : "v"(a), "v"(b)); return r; }
; DI void softmax_step_r(AttnSt& st, const float (&lg)[16], const KVT& t) {
;   float mx = NEGINF;
; #pragma unroll
;   for (int i = 0; i < 16; ++i) mx = fmaxf(mx, lg[i]);
;   mx = fmaxf(mx, shx32(mx));
;   if (__ballot(mx > NEGINF) == 0ull) return;
;   const float mnew = fmaxf(st.m, mx);
;   const float muse = (mnew == NEGINF) ? 0.f : mnew;
;   const float alpha = ex2(st.m - muse);
;   float pr[16]; float rs = 0.f;
; #pragma unroll
;   for (int i = 0; i < 16; ++i) { pr[i] = ex2(lg[i] - muse); rs += pr[i]; }
;   st.l = st.l * alpha + rs;
;   if (__ballot(mnew != st.m) != 0ull) {
; #pragma unroll
;     for (int i = 0; i < 16; ++i) { st.o0[i] *= alpha; st.o1[i] *= alpha; }
;   }
;   st.m = mnew;
; #pragma unroll
;   for (int s2 = 0; s2 < 2; ++s2) {
;     u32x4 pk; pk.x = pack2(pr[8 * s2], pr[8 * s2 + 1]); pk.y = pack2(pr[8 * s2 + 2], pr[8 * s2 + 3]); pk.z = pack2(pr[8 * s2 + 4], pr[8 * s2 + 5]); pk.w = pack2(pr[8 * s2 + 6], pr[8 * s2 + 7]);
;     const bf16x8 pb = __builtin_bit_cast(bf16x8, pk);
;     const bf16x8 va0 = __builtin_shufflevector(t.v[s2 * 4 + 0], t.v[s2 * 4 + 1], 0, 1, 2, 3, 4, 5, 6, 7);
;     st.o0 = MFMA32(va0, pb, st.o0);
;     const bf16x8 va1 = __builtin_shufflevector(t.v[s2 * 4 + 2], t.v[s2 * 4 + 3], 0, 1, 2, 3, 4, 5, 6, 7);
;     st.o1 = MFMA32(va1, pb, st.o1);
;   }
; }
.Lawin4_softmax:
	v_max3_f32 v118, v32, v33, v34
	v_max3_f32 v119, v40, v41, v42
	v_max3_f32 v120, v48, v49, v50
	v_max3_f32 v121, v56, v57, v58
	v_max3_f32 v118, v118, v35, v36
	v_max3_f32 v119, v119, v43, v44
	v_max3_f32 v120, v120, v51, v52
	v_max3_f32 v121, v121, v59, v60
	v_max3_f32 v118, v118, v37, v38
	v_max3_f32 v119, v119, v45, v46
	v_max3_f32 v120, v120, v53, v54
	v_max3_f32 v121, v121, v61, v62
	v_max_f32_e32 v118, v118, v39
	v_max_f32_e32 v119, v119, v47
	v_max_f32_e32 v120, v120, v55
	v_max_f32_e32 v121, v121, v63
	v_max3_f32 v118, v118, v119, v120
	v_max_f32_e32 v118, v118, v121
	v_mov_b32_e32 v119, v118
	v_mov_b32_e32 v120, v118
	s_nop 1
	v_permlane32_swap_b32_e32 v119, v120
	v_cndmask_b32_e64 v119, v119, v120, s[12:13]
	v_max_f32_e32 v118, v118, v119
	v_cndmask_b32_e64 v118, v199, v118, s[62:63]
	v_max_f32_e32 v119, v145, v118
	v_cmp_neq_f32_e32 vcc, v199, v119
	s_nop 1
	v_cndmask_b32_e32 v120, 0, v119, vcc
	v_sub_f32_e32 v121, v145, v120
	v_exp_f32_e32 v121, v121
	v_cndmask_b32_e64 v120, v181, v120, s[62:63]
	v_cmp_neq_f32_e32 vcc, v145, v119
	v_mov_b32_e32 v145, v119
	v_sub_f32_e32 v32, v32, v120
	v_sub_f32_e32 v33, v33, v120
	v_sub_f32_e32 v34, v34, v120
	v_sub_f32_e32 v35, v35, v120
	v_sub_f32_e32 v36, v36, v120
	v_sub_f32_e32 v37, v37, v120
	v_sub_f32_e32 v38, v38, v120
	v_sub_f32_e32 v39, v39, v120
	v_sub_f32_e32 v40, v40, v120
	v_sub_f32_e32 v41, v41, v120
	v_sub_f32_e32 v42, v42, v120
	v_sub_f32_e32 v43, v43, v120
	v_sub_f32_e32 v44, v44, v120
	v_sub_f32_e32 v45, v45, v120
	v_sub_f32_e32 v46, v46, v120
	v_sub_f32_e32 v47, v47, v120
	v_sub_f32_e32 v48, v48, v120
	v_sub_f32_e32 v49, v49, v120
	v_sub_f32_e32 v50, v50, v120
	v_sub_f32_e32 v51, v51, v120
	v_sub_f32_e32 v52, v52, v120
	v_sub_f32_e32 v53, v53, v120
	v_sub_f32_e32 v54, v54, v120
	v_sub_f32_e32 v55, v55, v120
	v_sub_f32_e32 v56, v56, v120
	v_sub_f32_e32 v57, v57, v120
	v_sub_f32_e32 v58, v58, v120
	v_sub_f32_e32 v59, v59, v120
	v_sub_f32_e32 v60, v60, v120
	v_sub_f32_e32 v61, v61, v120
	v_sub_f32_e32 v62, v62, v120
	v_sub_f32_e32 v63, v63, v120
	v_exp_f32_e32 v32, v32
	v_exp_f32_e32 v33, v33
	v_exp_f32_e32 v34, v34
	v_exp_f32_e32 v35, v35
	v_exp_f32_e32 v36, v36
	v_exp_f32_e32 v37, v37
	v_exp_f32_e32 v38, v38
	v_exp_f32_e32 v39, v39
	v_exp_f32_e32 v40, v40
	v_exp_f32_e32 v41, v41
	v_exp_f32_e32 v42, v42
	v_exp_f32_e32 v43, v43
	v_exp_f32_e32 v44, v44
	v_exp_f32_e32 v45, v45
	v_exp_f32_e32 v46, v46
	v_exp_f32_e32 v47, v47
	v_exp_f32_e32 v48, v48
	v_exp_f32_e32 v49, v49
	v_exp_f32_e32 v50, v50
	v_exp_f32_e32 v51, v51
	v_exp_f32_e32 v52, v52
	v_exp_f32_e32 v53, v53
	v_exp_f32_e32 v54, v54
	v_exp_f32_e32 v55, v55
	v_exp_f32_e32 v56, v56
	v_exp_f32_e32 v57, v57
	v_exp_f32_e32 v58, v58
	v_exp_f32_e32 v59, v59
	v_exp_f32_e32 v60, v60
	v_exp_f32_e32 v61, v61
	v_exp_f32_e32 v62, v62
	v_exp_f32_e32 v63, v63
	v_add_f32_e32 v122, v32, v33
	v_add_f32_e32 v123, v40, v41
	v_add_f32_e32 v124, v48, v49
	v_add_f32_e32 v125, v56, v57
	v_add_f32_e32 v122, v122, v34
	v_add_f32_e32 v123, v123, v42
	v_add_f32_e32 v124, v124, v50
	v_add_f32_e32 v125, v125, v58
	v_add_f32_e32 v122, v122, v35
	v_add_f32_e32 v123, v123, v43
	v_add_f32_e32 v124, v124, v51
	v_add_f32_e32 v125, v125, v59
	v_add_f32_e32 v122, v122, v36
	v_add_f32_e32 v123, v123, v44
	v_add_f32_e32 v124, v124, v52
	v_add_f32_e32 v125, v125, v60
	v_add_f32_e32 v122, v122, v37
	v_add_f32_e32 v123, v123, v45
	v_add_f32_e32 v124, v124, v53
	v_add_f32_e32 v125, v125, v61
	v_add_f32_e32 v122, v122, v38
	v_add_f32_e32 v123, v123, v46
	v_add_f32_e32 v124, v124, v54
	v_add_f32_e32 v125, v125, v62
	v_add_f32_e32 v122, v122, v39
	v_add_f32_e32 v123, v123, v47
	v_add_f32_e32 v124, v124, v55
	v_add_f32_e32 v125, v125, v63
	v_add_f32_e32 v122, v122, v123
	v_add_f32_e32 v124, v124, v125
	v_add_f32_e32 v122, v122, v124
	v_fma_f32 v144, v144, v121, v122
	s_cbranch_vccz .Lawin4_noscale
	v_mul_f32_e32 v0, v121, v0
	v_mul_f32_e32 v1, v121, v1
	v_mul_f32_e32 v2, v121, v2
	v_mul_f32_e32 v3, v121, v3
	v_mul_f32_e32 v4, v121, v4
	v_mul_f32_e32 v5, v121, v5
	v_mul_f32_e32 v6, v121, v6
	v_mul_f32_e32 v7, v121, v7
	v_mul_f32_e32 v8, v121, v8
	v_mul_f32_e32 v9, v121, v9
	v_mul_f32_e32 v10, v121, v10
	v_mul_f32_e32 v11, v121, v11
	v_mul_f32_e32 v12, v121, v12
	v_mul_f32_e32 v13, v121, v13
	v_mul_f32_e32 v14, v121, v14
	v_mul_f32_e32 v15, v121, v15
	v_mul_f32_e32 v16, v121, v16
	v_mul_f32_e32 v17, v121, v17
	v_mul_f32_e32 v18, v121, v18
	v_mul_f32_e32 v19, v121, v19
	v_mul_f32_e32 v20, v121, v20
	v_mul_f32_e32 v21, v121, v21
	v_mul_f32_e32 v22, v121, v22
	v_mul_f32_e32 v23, v121, v23
	v_mul_f32_e32 v24, v121, v24
	v_mul_f32_e32 v25, v121, v25
	v_mul_f32_e32 v26, v121, v26
	v_mul_f32_e32 v27, v121, v27
	v_mul_f32_e32 v28, v121, v28
	v_mul_f32_e32 v29, v121, v29
	v_mul_f32_e32 v30, v121, v30
	v_mul_f32_e32 v31, v121, v31
.Lawin4_noscale:
	v_cvt_pk_bf16_f32 v118, v32, v33
	v_cvt_pk_bf16_f32 v119, v34, v35
	v_cvt_pk_bf16_f32 v120, v36, v37
	v_cvt_pk_bf16_f32 v121, v38, v39
	v_cvt_pk_bf16_f32 v122, v40, v41
	v_cvt_pk_bf16_f32 v123, v42, v43
	v_cvt_pk_bf16_f32 v124, v44, v45
	v_cvt_pk_bf16_f32 v125, v46, v47
	v_cvt_pk_bf16_f32 v132, v48, v49
	v_cvt_pk_bf16_f32 v133, v50, v51
	v_cvt_pk_bf16_f32 v134, v52, v53
	v_cvt_pk_bf16_f32 v135, v54, v55
	v_cvt_pk_bf16_f32 v218, v56, v57
	v_cvt_pk_bf16_f32 v219, v58, v59
	v_cvt_pk_bf16_f32 v220, v60, v61
	v_cvt_pk_bf16_f32 v221, v62, v63
	s_waitcnt lgkmcnt(0)
	s_nop 1
	v_mfma_f32_32x32x16_bf16 v[0:15], v[146:149], v[118:121], v[0:15]
	v_mfma_f32_32x32x16_bf16 v[16:31], v[150:153], v[118:121], v[16:31]
	v_mfma_f32_32x32x16_bf16 v[0:15], v[154:157], v[122:125], v[0:15]
	v_mfma_f32_32x32x16_bf16 v[16:31], v[158:161], v[122:125], v[16:31]
	v_mfma_f32_32x32x16_bf16 v[0:15], v[162:165], v[132:135], v[0:15]
	v_mfma_f32_32x32x16_bf16 v[16:31], v[166:169], v[132:135], v[16:31]
	v_mfma_f32_32x32x16_bf16 v[0:15], v[170:173], v[218:221], v[0:15]
	v_mfma_f32_32x32x16_bf16 v[16:31], v[174:177], v[218:221], v[16:31]
.Lawin4_skip:
	s_add_u32 s64, s64, 0x4000
	s_cmp_eq_u32 s64, 0x1c000
	s_cselect_b32 s64, 0x10000, s64
	s_add_u32 s56, s56, 2
	s_cmp_le_u32 s56, s59
	s_cbranch_scc1 .Lawin4_loop
	s_nop 15
	s_waitcnt vmcnt(0)
